# v1 plus: attention steady loop LDS-DMA issue split by wave half (waves 4-7 issue at step top, waves 0-3 after QK)
# baseline (speedup 1.0000x reference)
; #define WAIT_BAR(N) asm volatile("s_waitcnt vmcnt(" #N ") lgkmcnt(0)\n\ts_barrier":::"memory")
;   #define DMA_K(t,slot) glds16(ksrc+(long)(t)*KVBLK*DM,(unsigned)__builtin_amdgcn_readfirstlane(kdst+(slot)))
;   #define DMA_V(t,slot) do{ glds16(vsrc+(long)(t)*KVBLK*DM,(unsigned)__builtin_amdgcn_readfirstlane(vdst+(slot))); glds16(vsrc+64+(long)(t)*KVBLK*DM,(unsigned)__builtin_amdgcn_readfirstlane(vdst2+(slot))); }while(0)
;   #define CMASK(P0,P1,t) do{int jb_=(t)-(NT-4); if(jb_>=0)cmask(P0,P1,jb_,qrel,hi);}while(0)
;   #define START(P0,P1) do{ resc=false; \
;     { _Pragma("unroll") for(int r=0;r<16;++r){P0[r]=fsub_s(P0[r],mhat);P1[r]=fsub_s(P1[r],mhat);} \
;       } \
;     _Pragma("unroll") for(int r=0;r<16;++r)P0[r]=__builtin_amdgcn_exp2f(P0[r]); }while(0)
;   #define ROT() do{sl_prev=sl_cur;sl_cur=sl_next;sl_next=(sl_next==(NSLOT-1)*SLOTB)?0:sl_next+SLOTB;}while(0)
;   #define CMASK(P0,P1,t) do{}while(0)
;   #define CMASK(P0,P1,t) do{int jb_=(t)-(NT-4); if(jb_>=0)cmask(P0,P1,jb_,qrel,hi);}while(0)
; template<int THRL> __device__ __forceinline__ void attn_unit(int b,int h,int qb,unsigned char*wsb,char*shm,float kmax,const int CMB,float lam){
;     ...
;   const float mhat=sqrtf(q2_)*kmax*1.004f+0.02f;
;   float l_reg=0.f;f32x16 o[2];o[0]=f32x16{};o[1]=f32x16{};f32x16 o2[2];o2[0]=f32x16{};o2[1]=f32x16{};const f32x16 negm=f32x16{};
;   const int qrel=wid*QBLK+r32;
;     ...
;   bool resc=false;
;     ...
;   f32x16 pA0,pA1,pB0,pB1;
;   int sl_prev=0,sl_cur=0,sl_next=SLOTB;
;     ...
;   DMA_K(2,2*SLOTB);
;   WAIT_BAR(4);
;   qkt(pA0,pA1,Kbase,qr,negm,r32,hi);asm volatile("s_nop 15\n\ts_nop 7":"+v"(pA0),"+v"(pA1));CMASK(pA0,pA1,0);
;   START(pA0,pA1);
;   _Pragma("unroll") for(int r=0;r<16;++r)pA1[r]=__builtin_amdgcn_exp2f(pA1[r]);
;   WAIT_BAR(0);
;   DMA_K(3,0);DMA_V(1,SLOTB);
;   ROT();
;   kload8(kf,kp0+sl_cur);
;   WAIT_BAR(3);
; __global__ void __launch_bounds__(NTHR, 2) fwd_megakernel(Args args_unused) {
;     ...
;                     const float kmax = 1.01f * sqrtf(__uint_as_float(__builtin_amdgcn_readfirstlane(__hip_atomic_load((unsigned*)(ws + WS_KMAX) + 2 * bh, __ATOMIC_RELAXED, __HIP_MEMORY_SCOPE_AGENT)))
;                                                    + __uint_as_float(__builtin_amdgcn_readfirstlane(__hip_atomic_load((unsigned*)(ws + WS_KMAX) + 2 * bh + 1, __ATOMIC_RELAXED, __HIP_MEMORY_SCOPE_AGENT))));
.LBB0_309:
	v_mov_b32_e32 v39, s6
	v_add_f32_e32 v39, s5, v39
	v_mul_f32_e32 v40, 0x4f800000, v39
	v_cmp_gt_f32_e32 vcc, s74, v39
	v_add_f32_e32 v37, v37, v38
	v_mul_f32_e32 v38, 0x4f800000, v37
	v_cndmask_b32_e32 v39, v39, v40, vcc
	v_sqrt_f32_e32 v40, v39
	s_waitcnt vmcnt(0) lgkmcnt(0)
	s_barrier
	s_cmp_lg_u32 0, -1
	s_mov_b32 s37, 0
	v_add_u32_e32 v41, -1, v40
	v_fma_f32 v42, -v41, v40, v39
	v_cmp_ge_f32_e64 s[4:5], 0, v42
	v_add_u32_e32 v42, 1, v40
	s_mov_b32 s6, 1
	v_cndmask_b32_e64 v41, v40, v41, s[4:5]
	v_fma_f32 v40, -v42, v40, v39
	v_cmp_lt_f32_e64 s[4:5], 0, v40
	s_nop 1
	v_cndmask_b32_e64 v40, v41, v42, s[4:5]
	v_mul_f32_e32 v41, 0x37800000, v40
	v_cndmask_b32_e32 v40, v40, v41, vcc
	v_cmp_class_f32_e32 vcc, v39, v237
	s_nop 1
	v_cndmask_b32_e32 v39, v40, v39, vcc
	v_cmp_gt_f32_e32 vcc, s74, v37
	v_lshlrev_b32_e32 v40, 1, v36
	v_and_b32_e32 v251, 32, v40
	v_cndmask_b32_e32 v37, v37, v38, vcc
	v_sqrt_f32_e32 v38, v37
	v_lshlrev_b32_e32 v40, 4, v36
	v_and_b32_e32 v40, 0xc0, v40
	v_lshl_or_b32 v246, v242, 8, v40
	v_add_u32_e32 v40, 0, v251
	v_add3_u32 v252, v40, v249, v246
	v_add_u32_e32 v40, -1, v38
	v_fma_f32 v41, -v40, v38, v37
	v_cmp_ge_f32_e64 s[4:5], 0, v41
	v_add_u32_e32 v41, 1, v38
	v_mul_f32_e32 v39, 0x3f8147ae, v39
	v_cndmask_b32_e64 v40, v38, v40, s[4:5]
	v_fma_f32 v38, -v41, v38, v37
	v_cmp_lt_f32_e64 s[4:5], 0, v38
	s_nop 1
	v_cndmask_b32_e64 v38, v40, v41, s[4:5]
	v_mul_f32_e32 v40, 0x37800000, v38
	v_cndmask_b32_e32 v38, v38, v40, vcc
	v_cmp_class_f32_e32 vcc, v37, v237
	s_mov_b64 s[4:5], 0x60000
	s_nop 0
	v_cndmask_b32_e32 v37, v38, v37, vcc
	v_mul_f32_e32 v37, v39, v37
	v_fmamk_f32 v247, v37, 0x3f808312, v238
	v_sub_f32_e32 v0, v0, v247
	v_sub_f32_e32 v1, v1, v247
	v_sub_f32_e32 v16, v16, v247
	v_sub_f32_e32 v17, v17, v247
	v_sub_f32_e32 v2, v2, v247
	v_sub_f32_e32 v18, v18, v247
	s_nop 0
	v_exp_f32_e32 v96, v0
	v_exp_f32_e32 v97, v1
	v_lshl_add_u64 v[0:1], v[32:33], 0, s[4:5]
	s_mov_b32 s4, m0
	s_mov_b32 m0, s3
	s_nop 0
	global_load_lds_dwordx4 v[0:1], off
	s_mov_b32 m0, s4
	s_mov_b64 s[4:5], 0x20000
	v_lshl_add_u64 v[0:1], v[34:35], 0, s[4:5]
	s_cselect_b32 s4, 0, 0
	s_add_i32 s1, s4, s1
	s_add_i32 s4, s1, 0x8000
	s_mov_b32 s5, m0
	s_mov_b32 m0, s4
	s_nop 0
	global_load_lds_dwordx4 v[0:1], off
	s_mov_b32 m0, s5
	s_mov_b64 s[4:5], 0x20080
	v_lshl_add_u64 v[0:1], v[34:35], 0, s[4:5]
	s_add_i32 s1, s1, 0xe000
	s_mov_b32 s4, m0
	s_mov_b32 m0, s1
	s_nop 0
	global_load_lds_dwordx4 v[0:1], off
	s_mov_b32 m0, s4
	ds_read_b128 v[204:207], v250 offset:8192
	ds_read_b128 v[200:203], v250 offset:8704
	ds_read_b128 v[196:199], v250 offset:10240
	ds_read_b128 v[192:195], v250 offset:10752
	ds_read_b128 v[188:191], v250 offset:12288
	ds_read_b128 v[184:187], v250 offset:12800
	ds_read_b128 v[180:183], v250 offset:14336
	ds_read_b128 v[176:179], v250 offset:14848
	v_sub_f32_e32 v3, v3, v247
	v_sub_f32_e32 v19, v19, v247
	v_sub_f32_e32 v4, v4, v247
	v_sub_f32_e32 v20, v20, v247
	v_sub_f32_e32 v5, v5, v247
	v_sub_f32_e32 v21, v21, v247
	v_sub_f32_e32 v6, v6, v247
	v_sub_f32_e32 v22, v22, v247
	v_sub_f32_e32 v7, v7, v247
	v_sub_f32_e32 v23, v23, v247
	v_sub_f32_e32 v8, v8, v247
	v_sub_f32_e32 v24, v24, v247
	v_sub_f32_e32 v9, v9, v247
	v_sub_f32_e32 v25, v25, v247
	v_sub_f32_e32 v10, v10, v247
	v_sub_f32_e32 v26, v26, v247
	v_sub_f32_e32 v11, v11, v247
	v_sub_f32_e32 v27, v27, v247
	v_sub_f32_e32 v12, v12, v247
	v_sub_f32_e32 v28, v28, v247
	v_sub_f32_e32 v13, v13, v247
	v_sub_f32_e32 v29, v29, v247
	v_sub_f32_e32 v14, v14, v247
	v_sub_f32_e32 v30, v30, v247
	v_sub_f32_e32 v15, v15, v247
	v_sub_f32_e32 v31, v31, v247
	v_exp_f32_e32 v98, v2
	v_exp_f32_e32 v99, v3
	v_exp_f32_e32 v100, v4
	v_exp_f32_e32 v101, v5
	v_exp_f32_e32 v102, v6
	v_exp_f32_e32 v103, v7
	v_exp_f32_e32 v104, v8
	v_exp_f32_e32 v105, v9
	v_exp_f32_e32 v106, v10
	v_exp_f32_e32 v107, v11
	v_exp_f32_e32 v108, v12
	v_exp_f32_e32 v109, v13
	v_exp_f32_e32 v110, v14
	v_exp_f32_e32 v111, v15
	v_exp_f32_e32 v80, v16
	v_exp_f32_e32 v81, v17
	v_exp_f32_e32 v82, v18
	v_exp_f32_e32 v83, v19
	v_exp_f32_e32 v84, v20
	v_exp_f32_e32 v85, v21
	v_exp_f32_e32 v86, v22
	v_exp_f32_e32 v87, v23
	v_exp_f32_e32 v88, v24
	v_exp_f32_e32 v89, v25
	v_exp_f32_e32 v90, v26
	v_exp_f32_e32 v91, v27
	v_exp_f32_e32 v92, v28
	v_exp_f32_e32 v93, v29
	v_exp_f32_e32 v94, v30
	v_exp_f32_e32 v95, v31
	s_waitcnt vmcnt(3) lgkmcnt(0)
	s_barrier
	v_and_b32_e32 v0, 3, v36
	s_andn2_b64 vcc, exec, s[54:55]
	v_lshlrev_b32_e32 v208, 4, v0
	s_cbranch_vccnz .LBB0_313
	s_lshl_b32 s1, s43, 6
	s_add_i32 s6, s79, s1
	s_lshr_b32 s4, s6, 7
	s_mov_b32 s5, s7
	s_lshl_b64 s[4:5], s[4:5], 8
	s_lshl_b64 s[36:37], s[68:69], 1
	s_add_u32 s4, s36, s4
	v_mov_b32_e32 v209, v221
	s_addc_u32 s5, s37, s5
	s_lshl_b32 s1, s95, 9
	v_lshl_add_u64 v[0:1], s[4:5], 0, v[208:209]
	s_and_b32 s1, s1, 0x18000
	s_lshl_b64 s[4:5], s[66:67], 1
	s_lshl_b64 s[36:37], s[6:7], 1
	v_lshl_or_b32 v2, v214, 11, s1
	s_add_u32 s1, s64, s36
	s_addc_u32 s6, s65, s37
	v_mov_b32_e32 v3, v221
	s_add_u32 s4, s1, s4
	v_lshl_add_u64 v[0:1], v[0:1], 0, v[2:3]
	s_addc_u32 s5, s6, s5
	v_mov_b32_e32 v64, 0
	s_mov_b32 s33, 6
	v_lshl_add_u64 v[210:211], s[64:65], 0, v[0:1]
	v_lshl_add_u64 v[212:213], s[4:5], 0, v[220:221]
	s_movk_i32 s36, 0x4000
	s_movk_i32 s42, 0x2000
	s_mov_b32 s5, 0
	v_mov_b32_e32 v0, 0
	v_mov_b32_e32 v1, v64
	v_mov_b32_e32 v2, v64
	v_mov_b32_e32 v3, v64
	v_mov_b32_e32 v4, v64
	v_mov_b32_e32 v5, v64
	v_mov_b32_e32 v6, v64
	v_mov_b32_e32 v7, v64
	v_mov_b32_e32 v8, v64
	v_mov_b32_e32 v9, v64
	v_mov_b32_e32 v10, v64
	v_mov_b32_e32 v11, v64
	v_mov_b32_e32 v12, v64
	v_mov_b32_e32 v13, v64
	v_mov_b32_e32 v14, v64
	v_mov_b32_e32 v15, v64
	v_mov_b32_e32 v16, 0
	v_mov_b32_e32 v17, v64
	v_mov_b32_e32 v18, v64
	v_mov_b32_e32 v19, v64
	v_mov_b32_e32 v20, v64
	v_mov_b32_e32 v21, v64
	v_mov_b32_e32 v22, v64
	v_mov_b32_e32 v23, v64
	v_mov_b32_e32 v24, v64
	v_mov_b32_e32 v25, v64
	v_mov_b32_e32 v26, v64
	v_mov_b32_e32 v27, v64
	v_mov_b32_e32 v28, v64
	v_mov_b32_e32 v29, v64
	v_mov_b32_e32 v30, v64
	v_mov_b32_e32 v31, v64
	v_mov_b32_e32 v32, 0
	v_mov_b32_e32 v33, v64
	v_mov_b32_e32 v34, v64
	v_mov_b32_e32 v35, v64
	v_mov_b32_e32 v36, v64
	v_mov_b32_e32 v37, v64
	v_mov_b32_e32 v38, v64
	v_mov_b32_e32 v39, v64
	v_mov_b32_e32 v40, v64
	v_mov_b32_e32 v41, v64
	v_mov_b32_e32 v42, v64
	v_mov_b32_e32 v43, v64
	v_mov_b32_e32 v44, v64
	v_mov_b32_e32 v45, v64
	v_mov_b32_e32 v46, v64
	v_mov_b32_e32 v47, v64
	v_mov_b32_e32 v48, 0
	v_mov_b32_e32 v49, v64
	v_mov_b32_e32 v50, v64
	v_mov_b32_e32 v51, v64
	v_mov_b32_e32 v52, v64
	v_mov_b32_e32 v53, v64
	v_mov_b32_e32 v54, v64
	v_mov_b32_e32 v55, v64
	v_mov_b32_e32 v56, v64
	v_mov_b32_e32 v57, v64
	v_mov_b32_e32 v58, v64
	v_mov_b32_e32 v59, v64
	v_mov_b32_e32 v60, v64
	v_mov_b32_e32 v61, v64
	v_mov_b32_e32 v62, v64
	v_mov_b32_e32 v63, v64
	v_readfirstlane_b32 s100, v230
	s_nop 3
	v_lshlrev_b32_e32 v143, 2, v230
	v_add_u32_e32 v143, 0x12800, v143
	ds_write_b32 v143, v246 offset:32768
	ds_write_b32 v143, v230
	ds_write_b32 v143, v231 offset:2048
	ds_write_b32 v143, v232 offset:4096
	ds_write_b32 v143, v233 offset:6144
	ds_write_b32 v143, v234 offset:8192
	ds_write_b32 v143, v235 offset:10240
	ds_write_b32 v143, v236 offset:12288
	ds_write_b32 v143, v237 offset:14336
	ds_write_b32 v143, v238 offset:16384
	ds_write_b32 v143, v239 offset:18432
	ds_write_b32 v143, v240 offset:20480
	ds_write_b32 v143, v241 offset:22528
	ds_write_b32 v143, v242 offset:24576
	ds_write_b32 v143, v243 offset:26624
	ds_write_b32 v143, v244 offset:28672
	ds_write_b32 v143, v245 offset:30720
	v_mov_b32_e32 v246, v143
	v_xor_b32_e32 v230, 0x80000000, v247
	v_mov_b32_e32 v231, v230
	v_mov_b32_e32 v232, v230
	v_mov_b32_e32 v233, v230
	v_mov_b32_e32 v234, v230
	v_mov_b32_e32 v235, v230
	v_mov_b32_e32 v236, v230
	v_mov_b32_e32 v237, v230
	v_mov_b32_e32 v238, v230
	v_mov_b32_e32 v239, v230
	v_mov_b32_e32 v240, v230
	v_mov_b32_e32 v241, v230
	v_mov_b32_e32 v242, v230
	v_mov_b32_e32 v243, v230
	v_mov_b32_e32 v244, v230
	v_mov_b32_e32 v245, v230
	s_waitcnt lgkmcnt(0)
.LBB0_311:
	s_mov_b32 s37, s36
	s_mov_b32 s4, s33
	s_mov_b32 s1, s42
	s_cmp_lt_u32 s100, 0x100
	s_cbranch_scc1 .Lattn_y1_skip
	s_mov_b32 s99, m0
	v_lshl_add_u64 v[224:225], v[212:213], 0, s[48:49]
	v_lshl_add_u64 v[228:229], v[224:225], 0, s[10:11]
	s_add_i32 s98, s42, s3
	s_mov_b32 m0, s98
	s_nop 0
	global_load_lds_dwordx4 v[228:229], off
	v_lshl_add_u64 v[226:227], v[210:211], 0, s[48:49]
	v_lshl_add_u64 v[228:229], v[226:227], 0, s[12:13]
	s_add_i32 s98, s36, s97
	s_mov_b32 m0, s98
	s_nop 0
	global_load_lds_dwordx4 v[228:229], off
	v_lshl_add_u64 v[228:229], v[226:227], 0, s[14:15]
	s_add_i32 s98, s36, s96
	s_mov_b32 m0, s98
	s_nop 0
	global_load_lds_dwordx4 v[228:229], off
	s_mov_b32 m0, s99
.Lattn_y1_skip:
	v_add_u32_e32 v209, s5, v252
	ds_read_b64_tr_b16 v[216:217], v209 offset:24576
	ds_read_b64_tr_b16 v[218:219], v209 offset:25088
	v_add_f32_e32 v65, v96, v97
	v_add_f32_e32 v65, v98, v65
	v_add_f32_e32 v65, v99, v65
	v_add_f32_e32 v65, v100, v65
	v_add_f32_e32 v65, v101, v65
	v_cvt_pk_bf16_f32 v172, v96, v97
	v_cvt_pk_bf16_f32 v173, v98, v99
	s_waitcnt lgkmcnt(9)
	v_mfma_f32_32x32x16_bf16 v[128:143], v[204:207], v[156:159], v[230:245]
	ds_read_b64_tr_b16 v[204:205], v209 offset:28672
	ds_read_b64_tr_b16 v[206:207], v209 offset:29184
	v_add_f32_e32 v65, v102, v65
	v_add_f32_e32 v65, v103, v65
	v_add_f32_e32 v65, v104, v65
	v_add_f32_e32 v65, v105, v65
	v_cvt_pk_bf16_f32 v174, v100, v101
	v_cvt_pk_bf16_f32 v175, v102, v103
	s_waitcnt lgkmcnt(10)
	v_mfma_f32_32x32x16_bf16 v[112:127], v[200:203], v[156:159], v[230:245]
	ds_read_b64_tr_b16 v[74:75], v209 offset:25600
	ds_read_b64_tr_b16 v[76:77], v209 offset:26112
	v_add_f32_e32 v65, v106, v65
	v_add_f32_e32 v65, v107, v65
	v_add_f32_e32 v65, v108, v65
	v_add_f32_e32 v65, v109, v65
	v_cvt_pk_bf16_f32 v168, v104, v105
	v_cvt_pk_bf16_f32 v169, v106, v107
	s_waitcnt lgkmcnt(11)
	v_mfma_f32_32x32x16_bf16 v[128:143], v[196:199], v[152:155], v[128:143]
	ds_read_b64_tr_b16 v[70:71], v209 offset:29696
	ds_read_b64_tr_b16 v[72:73], v209 offset:30208
	v_add_f32_e32 v65, v110, v65
	v_add_f32_e32 v65, v111, v65
	v_add_f32_e32 v65, v80, v65
	v_add_f32_e32 v65, v81, v65
	v_cvt_pk_bf16_f32 v170, v108, v109
	v_cvt_pk_bf16_f32 v171, v110, v111
	s_waitcnt lgkmcnt(12)
	v_mfma_f32_32x32x16_bf16 v[112:127], v[192:195], v[152:155], v[112:127]
	ds_read_b64_tr_b16 v[66:67], v209 offset:26624
	ds_read_b64_tr_b16 v[68:69], v209 offset:27136
	v_add_f32_e32 v65, v82, v65
	v_add_f32_e32 v65, v83, v65
	v_add_f32_e32 v65, v84, v65
	v_add_f32_e32 v65, v85, v65
	v_cvt_pk_bf16_f32 v164, v80, v81
	v_cvt_pk_bf16_f32 v165, v82, v83
	s_waitcnt lgkmcnt(13)
	v_mfma_f32_32x32x16_bf16 v[128:143], v[188:191], v[148:151], v[128:143]
	ds_read_b64_tr_b16 v[100:101], v209 offset:30720
	ds_read_b64_tr_b16 v[102:103], v209 offset:31232
	v_add_f32_e32 v65, v86, v65
	v_add_f32_e32 v65, v87, v65
	v_add_f32_e32 v65, v88, v65
	v_add_f32_e32 v65, v89, v65
	v_cvt_pk_bf16_f32 v166, v84, v85
	v_cvt_pk_bf16_f32 v167, v86, v87
	s_waitcnt lgkmcnt(14)
	v_mfma_f32_32x32x16_bf16 v[112:127], v[184:187], v[148:151], v[112:127]
	ds_read_b64_tr_b16 v[96:97], v209 offset:27648
	ds_read_b64_tr_b16 v[98:99], v209 offset:28160
	v_add_f32_e32 v65, v90, v65
	v_add_f32_e32 v65, v91, v65
	v_add_f32_e32 v65, v92, v65
	v_add_f32_e32 v65, v93, v65
	v_cvt_pk_bf16_f32 v160, v88, v89
	v_cvt_pk_bf16_f32 v161, v90, v91
	s_waitcnt lgkmcnt(14)
	v_mfma_f32_32x32x16_bf16 v[128:143], v[180:183], v[144:147], v[128:143]
	ds_read_b64_tr_b16 v[86:87], v209 offset:31744
	ds_read_b64_tr_b16 v[88:89], v209 offset:32256
	v_add_f32_e32 v65, v94, v65
	v_add_f32_e32 v65, v95, v65
	v_add_f32_e32 v65, 0, v65
	v_cvt_pk_bf16_f32 v162, v92, v93
	v_cvt_pk_bf16_f32 v163, v94, v95
	v_mfma_f32_32x32x16_bf16 v[112:127], v[176:179], v[144:147], v[112:127]
	s_cmp_ge_u32 s100, 0x100
	s_cbranch_scc1 .Lattn_x1_skip
	v_lshl_add_u64 v[190:191], v[212:213], 0, s[48:49]
	v_lshl_add_u64 v[78:79], v[190:191], 0, s[10:11]
	s_add_i32 s5, s42, s3
	s_mov_b32 s6, m0
	s_mov_b32 m0, s5
	s_nop 0
	global_load_lds_dwordx4 v[78:79], off
	s_mov_b32 m0, s6
	v_lshl_add_u64 v[188:189], v[210:211], 0, s[48:49]
	v_lshl_add_u64 v[78:79], v[188:189], 0, s[12:13]
	s_add_i32 s5, s36, s97
	s_mov_b32 s6, m0
	s_mov_b32 m0, s5
	s_nop 0
	global_load_lds_dwordx4 v[78:79], off
	s_mov_b32 m0, s6
	v_lshl_add_u64 v[78:79], v[188:189], 0, s[14:15]
	s_add_i32 s5, s36, s96
	s_mov_b32 s6, m0
	s_mov_b32 m0, s5
	s_nop 0
	global_load_lds_dwordx4 v[78:79], off
	s_mov_b32 m0, s6
.Lattn_x1_skip:
	s_waitcnt lgkmcnt(14)
	v_mfma_f32_32x32x16_bf16 v[32:47], v[172:175], v[216:219], v[32:47]
	v_exp_f32_e32 v128, v128
	v_exp_f32_e32 v129, v129
	ds_read_b64_tr_b16 v[90:91], v209 offset:49152
	ds_read_b64_tr_b16 v[92:93], v209 offset:49664
	s_waitcnt lgkmcnt(14)
	v_mfma_f32_32x32x16_bf16 v[48:63], v[172:175], v[204:207], v[48:63]
	v_exp_f32_e32 v130, v130
	v_exp_f32_e32 v131, v131
	ds_read_b64_tr_b16 v[104:105], v209 offset:53248
	ds_read_b64_tr_b16 v[106:107], v209 offset:53760
	v_add_u32_e32 v94, s37, v250
	ds_read_b128 v[82:85], v94
	ds_read_b128 v[78:81], v94 offset:512
	s_waitcnt lgkmcnt(14)
	v_mfma_f32_32x32x16_bf16 v[32:47], v[168:171], v[74:77], v[32:47]
	v_exp_f32_e32 v132, v132
	v_exp_f32_e32 v133, v133
	ds_read_b64_tr_b16 v[108:109], v209 offset:50176
	ds_read_b64_tr_b16 v[110:111], v209 offset:50688
	ds_read_b128 v[184:187], v94 offset:2048
	ds_read_b128 v[176:179], v94 offset:2560
	v_mfma_f32_32x32x16_bf16 v[48:63], v[168:171], v[70:73], v[48:63]
	v_exp_f32_e32 v134, v134
	v_exp_f32_e32 v135, v135
	ds_read_b64_tr_b16 v[192:193], v209 offset:54272
	ds_read_b64_tr_b16 v[194:195], v209 offset:54784
	ds_read_b128 v[180:183], v94 offset:4096
	ds_read_b128 v[70:73], v94 offset:4608
	s_waitcnt lgkmcnt(14)
	v_mfma_f32_32x32x16_bf16 v[32:47], v[164:167], v[66:69], v[32:47]
	v_exp_f32_e32 v136, v136
	v_exp_f32_e32 v137, v137
	ds_read_b64_tr_b16 v[196:197], v209 offset:51200
	ds_read_b64_tr_b16 v[198:199], v209 offset:51712
	ds_read_b128 v[74:77], v94 offset:6144
	ds_read_b128 v[66:69], v94 offset:6656
	v_mfma_f32_32x32x16_bf16 v[48:63], v[164:167], v[100:103], v[48:63]
	v_exp_f32_e32 v138, v138
	v_exp_f32_e32 v139, v139
	ds_read_b64_tr_b16 v[100:101], v209 offset:55296
	ds_read_b64_tr_b16 v[102:103], v209 offset:55808
	v_mfma_f32_32x32x16_bf16 v[32:47], v[160:163], v[96:99], v[32:47]
	v_exp_f32_e32 v140, v140
	v_exp_f32_e32 v141, v141
	ds_read_b64_tr_b16 v[94:95], v209 offset:52224
	ds_read_b64_tr_b16 v[96:97], v209 offset:52736
	v_mfma_f32_32x32x16_bf16 v[48:63], v[160:163], v[86:89], v[48:63]
	v_exp_f32_e32 v142, v142
	v_exp_f32_e32 v143, v143
	ds_read_b64_tr_b16 v[86:87], v209 offset:56320
	ds_read_b64_tr_b16 v[88:89], v209 offset:56832
	s_waitcnt lgkmcnt(14)
	v_mfma_f32_32x32x16_bf16 v[0:15], v[172:175], v[90:93], v[0:15]
	v_exp_f32_e32 v112, v112
	v_exp_f32_e32 v113, v113
	v_mfma_f32_32x32x16_bf16 v[16:31], v[172:175], v[104:107], v[16:31]
	v_exp_f32_e32 v114, v114
	v_exp_f32_e32 v115, v115
	v_mfma_f32_32x32x16_bf16 v[0:15], v[168:171], v[108:111], v[0:15]
	v_exp_f32_e32 v116, v116
	v_exp_f32_e32 v117, v117
	s_waitcnt lgkmcnt(12)
	v_mfma_f32_32x32x16_bf16 v[16:31], v[168:171], v[192:195], v[16:31]
	v_exp_f32_e32 v118, v118
	v_exp_f32_e32 v119, v119
	s_waitcnt lgkmcnt(8)
	v_mfma_f32_32x32x16_bf16 v[0:15], v[164:167], v[196:199], v[0:15]
	v_exp_f32_e32 v120, v120
	v_exp_f32_e32 v121, v121
	s_waitcnt lgkmcnt(4)
	v_mfma_f32_32x32x16_bf16 v[16:31], v[164:167], v[100:103], v[16:31]
	v_exp_f32_e32 v122, v122
	v_exp_f32_e32 v123, v123
	s_waitcnt lgkmcnt(2)
	v_mfma_f32_32x32x16_bf16 v[0:15], v[160:163], v[94:97], v[0:15]
	v_exp_f32_e32 v124, v124
	v_exp_f32_e32 v125, v125
	s_waitcnt lgkmcnt(0)
	v_mfma_f32_32x32x16_bf16 v[16:31], v[160:163], v[86:89], v[16:31]
	v_exp_f32_e32 v126, v126
	v_exp_f32_e32 v127, v127
	s_waitcnt vmcnt(3) lgkmcnt(0)
	s_barrier
	s_add_i32 s5, s36, 0x2000
	s_cmpk_lg_i32 s36, 0x4000
	s_cselect_b32 s42, s5, 0
	s_cmp_lt_u32 s100, 0x100
	s_cbranch_scc1 .Lattn_y2_skip
	s_mov_b32 s99, m0
	v_lshl_add_u64 v[228:229], v[224:225], 0, s[16:17]
	s_add_i32 s98, s36, s3
	s_mov_b32 m0, s98
	s_nop 0
	global_load_lds_dwordx4 v[228:229], off
	v_lshl_add_u64 v[228:229], v[226:227], 0, s[18:19]
	s_add_i32 s98, s42, s97
	s_mov_b32 m0, s98
	s_nop 0
	global_load_lds_dwordx4 v[228:229], off
	v_lshl_add_u64 v[228:229], v[226:227], 0, s[20:21]
	s_add_i32 s98, s42, s96
	s_mov_b32 m0, s98
	s_nop 0
	global_load_lds_dwordx4 v[228:229], off
	s_mov_b32 m0, s99
.Lattn_y2_skip:
	v_add_u32_e32 v209, s1, v252
	ds_read_b64_tr_b16 v[192:193], v209 offset:24576
	ds_read_b64_tr_b16 v[194:195], v209 offset:25088
	v_mfma_f32_32x32x16_bf16 v[96:111], v[82:85], v[156:159], v[230:245]
	v_add_f32_e32 v86, v128, v129
	v_add_f32_e32 v86, v130, v86
	v_add_f32_e32 v86, v131, v86
	v_add_f32_e32 v86, v132, v86
	v_add_f32_e32 v86, v133, v86
	v_cvt_pk_bf16_f32 v172, v128, v129
	v_cvt_pk_bf16_f32 v173, v130, v131
	ds_read_b64_tr_b16 v[196:197], v209 offset:28672
	ds_read_b64_tr_b16 v[198:199], v209 offset:29184
	v_add_f32_e32 v82, v134, v86
	v_add_f32_e32 v82, v135, v82
	v_add_f32_e32 v82, v136, v82
	v_add_f32_e32 v128, v137, v82
	v_mfma_f32_32x32x16_bf16 v[80:95], v[78:81], v[156:159], v[230:245]
	v_cvt_pk_bf16_f32 v174, v132, v133
	v_cvt_pk_bf16_f32 v175, v134, v135
	ds_read_b64_tr_b16 v[216:217], v209 offset:25600
	ds_read_b64_tr_b16 v[218:219], v209 offset:26112
	v_mfma_f32_32x32x16_bf16 v[96:111], v[184:187], v[152:155], v[96:111]
	v_add_f32_e32 v78, v138, v128
	v_add_f32_e32 v78, v139, v78
	v_add_f32_e32 v78, v140, v78
	v_add_f32_e32 v78, v141, v78
	v_cvt_pk_bf16_f32 v168, v136, v137
	v_cvt_pk_bf16_f32 v169, v138, v139
	ds_read_b64_tr_b16 v[136:137], v209 offset:29696
	ds_read_b64_tr_b16 v[138:139], v209 offset:30208
	v_mfma_f32_32x32x16_bf16 v[80:95], v[176:179], v[152:155], v[80:95]
	v_add_f32_e32 v78, v142, v78
	v_add_f32_e32 v78, v143, v78
	v_add_f32_e32 v78, v112, v78
	v_add_f32_e32 v78, v113, v78
	v_cvt_pk_bf16_f32 v170, v140, v141
	v_cvt_pk_bf16_f32 v171, v142, v143
	ds_read_b64_tr_b16 v[132:133], v209 offset:26624
	ds_read_b64_tr_b16 v[134:135], v209 offset:27136
	v_mfma_f32_32x32x16_bf16 v[96:111], v[180:183], v[148:151], v[96:111]
	v_add_f32_e32 v78, v114, v78
	v_add_f32_e32 v78, v115, v78
	v_add_f32_e32 v78, v116, v78
	v_add_f32_e32 v78, v117, v78
	v_cvt_pk_bf16_f32 v164, v112, v113
	v_cvt_pk_bf16_f32 v165, v114, v115
	ds_read_b64_tr_b16 v[128:129], v209 offset:30720
	ds_read_b64_tr_b16 v[130:131], v209 offset:31232
	v_mfma_f32_32x32x16_bf16 v[80:95], v[70:73], v[148:151], v[80:95]
	v_add_f32_e32 v78, v118, v78
	v_add_f32_e32 v78, v119, v78
	v_add_f32_e32 v78, v120, v78
	v_add_f32_e32 v78, v121, v78
	v_cvt_pk_bf16_f32 v166, v116, v117
	v_cvt_pk_bf16_f32 v167, v118, v119
	ds_read_b64_tr_b16 v[112:113], v209 offset:27648
	ds_read_b64_tr_b16 v[114:115], v209 offset:28160
	v_mfma_f32_32x32x16_bf16 v[96:111], v[74:77], v[144:147], v[96:111]
	v_add_f32_e32 v70, v122, v78
	v_add_f32_e32 v70, v123, v70
	v_add_f32_e32 v70, v124, v70
	v_add_f32_e32 v78, v125, v70
	v_cvt_pk_bf16_f32 v160, v120, v121
	v_cvt_pk_bf16_f32 v161, v122, v123
	ds_read_b64_tr_b16 v[70:71], v209 offset:31744
	ds_read_b64_tr_b16 v[72:73], v209 offset:32256
	v_mfma_f32_32x32x16_bf16 v[80:95], v[66:69], v[144:147], v[80:95]
	v_add_f32_e32 v74, v126, v78
	v_add_f32_e32 v74, v127, v74
	v_add_f32_e32 v74, 0, v74
	v_cvt_pk_bf16_f32 v162, v124, v125
	v_cvt_pk_bf16_f32 v163, v126, v127
	s_cmp_ge_u32 s100, 0x100
	s_cbranch_scc1 .Lattn_x2_skip
	v_lshl_add_u64 v[66:67], v[190:191], 0, s[16:17]
	s_add_i32 s1, s36, s3
	s_mov_b32 s5, m0
	s_mov_b32 m0, s1
	s_nop 0
	global_load_lds_dwordx4 v[66:67], off
	s_mov_b32 m0, s5
	v_lshl_add_u64 v[66:67], v[188:189], 0, s[18:19]
	s_add_i32 s1, s42, s97
	s_mov_b32 s5, m0
	s_mov_b32 m0, s1
	s_nop 0
	global_load_lds_dwordx4 v[66:67], off
	s_mov_b32 m0, s5
	v_lshl_add_u64 v[66:67], v[188:189], 0, s[20:21]
	s_add_i32 s1, s42, s96
	s_mov_b32 s5, m0
	s_mov_b32 m0, s1
	s_nop 0
	global_load_lds_dwordx4 v[66:67], off
	s_mov_b32 m0, s5
; #define WAIT_BAR(N) asm volatile("s_waitcnt vmcnt(" #N ") lgkmcnt(0)\n\ts_barrier":::"memory")
;   #define RESC() do{ if(resc){ asm volatile("s_waitcnt lgkmcnt(0)":::"memory"); \
;       _Pragma("unroll") for(int d_=0;d_<2;++d_) _Pragma("unroll") for(int r=0;r<16;++r){const float f_=wsf[crow(r,hi)];o[d_][r]*=f_;o2[d_][r]*=f_;} } }while(0)
;   #define ROT() do{sl_prev=sl_cur;sl_cur=sl_next;sl_next=(sl_next==(NSLOT-1)*SLOTB)?0:sl_next+SLOTB;}while(0)
; template<int THRL> __device__ __forceinline__ void attn_unit(int b,int h,int qb,unsigned char*wsb,char*shm,float kmax,const int CMB,float lam){
;     ...
;   int t=1;
;     ...
;   for(;t+5<NT;t+=2){
;     STEP(pB0,pB1,pA0,pA1,t,true,true,true);     WAIT_BAR(3); RESC(); ROT();
;     STEP(pA0,pA1,pB0,pB1,t+1,true,true,true);   WAIT_BAR(3); RESC(); ROT();
;   }
.Lattn_x2_skip:
	s_waitcnt lgkmcnt(14)
	v_mfma_f32_32x32x16_bf16 v[32:47], v[172:175], v[192:195], v[32:47]
	v_exp_f32_e32 v96, v96
	v_exp_f32_e32 v97, v97
	ds_read_b64_tr_b16 v[66:67], v209 offset:49152
	ds_read_b64_tr_b16 v[68:69], v209 offset:49664
	s_waitcnt lgkmcnt(14)
	v_mfma_f32_32x32x16_bf16 v[48:63], v[172:175], v[196:199], v[48:63]
	v_exp_f32_e32 v98, v98
	v_exp_f32_e32 v99, v99
	ds_read_b64_tr_b16 v[76:77], v209 offset:53248
	ds_read_b64_tr_b16 v[78:79], v209 offset:53760
	v_add_u32_e32 v75, s42, v250
	ds_read_b128 v[204:207], v75
	ds_read_b128 v[200:203], v75 offset:512
	s_waitcnt lgkmcnt(14)
	v_mfma_f32_32x32x16_bf16 v[32:47], v[168:171], v[216:219], v[32:47]
	v_exp_f32_e32 v100, v100
	v_exp_f32_e32 v101, v101
	ds_read_b64_tr_b16 v[116:117], v209 offset:50176
	ds_read_b64_tr_b16 v[118:119], v209 offset:50688
	ds_read_b128 v[196:199], v75 offset:2048
	ds_read_b128 v[192:195], v75 offset:2560
	v_mfma_f32_32x32x16_bf16 v[48:63], v[168:171], v[136:139], v[48:63]
	v_exp_f32_e32 v102, v102
	v_exp_f32_e32 v103, v103
	ds_read_b64_tr_b16 v[120:121], v209 offset:54272
	ds_read_b64_tr_b16 v[122:123], v209 offset:54784
	ds_read_b128 v[188:191], v75 offset:4096
	ds_read_b128 v[184:187], v75 offset:4608
	s_waitcnt lgkmcnt(14)
	v_mfma_f32_32x32x16_bf16 v[32:47], v[164:167], v[132:135], v[32:47]
	v_exp_f32_e32 v104, v104
	v_exp_f32_e32 v105, v105
	ds_read_b64_tr_b16 v[124:125], v209 offset:51200
	ds_read_b64_tr_b16 v[126:127], v209 offset:51712
	ds_read_b128 v[180:183], v75 offset:6144
	ds_read_b128 v[176:179], v75 offset:6656
	v_mfma_f32_32x32x16_bf16 v[48:63], v[164:167], v[128:131], v[48:63]
	v_exp_f32_e32 v106, v106
	v_exp_f32_e32 v107, v107
	ds_read_b64_tr_b16 v[128:129], v209 offset:55296
	ds_read_b64_tr_b16 v[130:131], v209 offset:55808
	v_mfma_f32_32x32x16_bf16 v[32:47], v[160:163], v[112:115], v[32:47]
	v_exp_f32_e32 v108, v108
	v_exp_f32_e32 v109, v109
	ds_read_b64_tr_b16 v[112:113], v209 offset:52224
	ds_read_b64_tr_b16 v[114:115], v209 offset:52736
	v_mfma_f32_32x32x16_bf16 v[48:63], v[160:163], v[70:73], v[48:63]
	v_exp_f32_e32 v110, v110
	v_exp_f32_e32 v111, v111
	ds_read_b64_tr_b16 v[70:71], v209 offset:56320
	ds_read_b64_tr_b16 v[72:73], v209 offset:56832
	s_waitcnt lgkmcnt(14)
	v_mfma_f32_32x32x16_bf16 v[0:15], v[172:175], v[66:69], v[0:15]
	v_exp_f32_e32 v80, v80
	v_exp_f32_e32 v81, v81
	v_mfma_f32_32x32x16_bf16 v[16:31], v[172:175], v[76:79], v[16:31]
	v_exp_f32_e32 v82, v82
	v_exp_f32_e32 v83, v83
	v_mfma_f32_32x32x16_bf16 v[0:15], v[168:171], v[116:119], v[0:15]
	v_exp_f32_e32 v84, v84
	v_exp_f32_e32 v85, v85
	s_waitcnt lgkmcnt(12)
	v_mfma_f32_32x32x16_bf16 v[16:31], v[168:171], v[120:123], v[16:31]
	v_exp_f32_e32 v86, v86
	v_exp_f32_e32 v87, v87
	s_waitcnt lgkmcnt(8)
	v_mfma_f32_32x32x16_bf16 v[0:15], v[164:167], v[124:127], v[0:15]
	v_exp_f32_e32 v88, v88
	v_exp_f32_e32 v89, v89
	s_waitcnt lgkmcnt(4)
	v_mfma_f32_32x32x16_bf16 v[16:31], v[164:167], v[128:131], v[16:31]
	v_exp_f32_e32 v90, v90
	v_exp_f32_e32 v91, v91
	s_waitcnt lgkmcnt(2)
	v_mfma_f32_32x32x16_bf16 v[0:15], v[160:163], v[112:115], v[0:15]
	v_exp_f32_e32 v92, v92
	v_exp_f32_e32 v93, v93
	s_waitcnt lgkmcnt(0)
	v_mfma_f32_32x32x16_bf16 v[16:31], v[160:163], v[70:73], v[16:31]
	v_exp_f32_e32 v94, v94
	v_exp_f32_e32 v95, v95
	s_add_i32 s1, s42, 0x2000
	s_waitcnt vmcnt(3) lgkmcnt(0)
	s_barrier
	s_cmpk_lg_i32 s42, 0x4000
	v_add_f32_e32 v64, v64, v65
	s_mov_b32 s5, s36
	s_cselect_b32 s36, s1, 0
	s_add_i32 s33, s33, 2
	v_lshl_add_u64 v[210:211], v[210:211], 0, s[22:23]
	v_lshl_add_u64 v[212:213], v[212:213], 0, s[22:23]
	s_cmp_ge_u32 s33, s89
	v_add_f32_e32 v64, v64, v74
	s_cbranch_scc0 .LBB0_311
	ds_read_b32 v230, v246
	ds_read_b32 v231, v246 offset:2048
	ds_read_b32 v232, v246 offset:4096
	ds_read_b32 v233, v246 offset:6144
	ds_read_b32 v234, v246 offset:8192
	ds_read_b32 v235, v246 offset:10240
	ds_read_b32 v236, v246 offset:12288
	ds_read_b32 v237, v246 offset:14336
	ds_read_b32 v238, v246 offset:16384
	ds_read_b32 v239, v246 offset:18432
	ds_read_b32 v240, v246 offset:20480
	ds_read_b32 v241, v246 offset:22528
	ds_read_b32 v242, v246 offset:24576
	ds_read_b32 v243, v246 offset:26624
	ds_read_b32 v244, v246 offset:28672
	ds_read_b32 v245, v246 offset:30720
	ds_read_b32 v246, v246 offset:32768
	s_waitcnt lgkmcnt(0)
	s_add_i32 s6, s4, -3
	s_branch .LBB0_314

; __global__ void __launch_bounds__(NTHR, 2) fwd_megakernel(Args args_unused) {
	.amdhsa_kernel _Z14fwd_megakernel4Args
		.amdhsa_group_segment_fixed_size 0
		.amdhsa_private_segment_fixed_size 0
		.amdhsa_kernarg_size 488
		.amdhsa_user_sgpr_count 2
		.amdhsa_user_sgpr_dispatch_ptr 0
		.amdhsa_user_sgpr_queue_ptr 0
		.amdhsa_user_sgpr_kernarg_segment_ptr 1
		.amdhsa_user_sgpr_dispatch_id 0
		.amdhsa_user_sgpr_kernarg_preload_length 0
		.amdhsa_user_sgpr_kernarg_preload_offset 0
		.amdhsa_user_sgpr_private_segment_size 0
		.amdhsa_uses_dynamic_stack 0
		.amdhsa_enable_private_segment 0
		.amdhsa_system_sgpr_workgroup_id_x 1
		.amdhsa_system_sgpr_workgroup_id_y 0
		.amdhsa_system_sgpr_workgroup_id_z 0
		.amdhsa_system_sgpr_workgroup_info 0
		.amdhsa_system_vgpr_workitem_id 2
		.amdhsa_next_free_vgpr 255
		.amdhsa_next_free_sgpr 102
		.amdhsa_accum_offset 256
		.amdhsa_reserve_vcc 1
		.amdhsa_float_round_mode_32 0
		.amdhsa_float_round_mode_16_64 0
		.amdhsa_float_denorm_mode_32 3
		.amdhsa_float_denorm_mode_16_64 3
		.amdhsa_dx10_clamp 1
		.amdhsa_ieee_mode 1
		.amdhsa_fp16_overflow 0
		.amdhsa_tg_split 0
		.amdhsa_exception_fp_ieee_invalid_op 0
		.amdhsa_exception_fp_denorm_src 0
		.amdhsa_exception_fp_ieee_div_zero 0
		.amdhsa_exception_fp_ieee_overflow 0
		.amdhsa_exception_fp_ieee_underflow 0
		.amdhsa_exception_fp_ieee_inexact 0
		.amdhsa_exception_int_div_zero 0
	.end_amdhsa_kernel

; __global__ void __launch_bounds__(NTHR, 2) fwd_megakernel(Args args_unused) {
amdhsa.kernels:
  - .agpr_count:     0
    .args:
      - .offset:         0
        .size:           232
        .value_kind:     by_value
      - .offset:         232
        .size:           4
        .value_kind:     hidden_block_count_x
      - .offset:         236
        .size:           4
        .value_kind:     hidden_block_count_y
      - .offset:         240
        .size:           4
        .value_kind:     hidden_block_count_z
      - .offset:         244
        .size:           2
        .value_kind:     hidden_group_size_x
      - .offset:         246
        .size:           2
        .value_kind:     hidden_group_size_y
      - .offset:         248
        .size:           2
        .value_kind:     hidden_group_size_z
      - .offset:         250
        .size:           2
        .value_kind:     hidden_remainder_x
      - .offset:         252
        .size:           2
        .value_kind:     hidden_remainder_y
      - .offset:         254
        .size:           2
        .value_kind:     hidden_remainder_z
      - .offset:         272
        .size:           8
        .value_kind:     hidden_global_offset_x
      - .offset:         280
        .size:           8
        .value_kind:     hidden_global_offset_y
      - .offset:         288
        .size:           8
        .value_kind:     hidden_global_offset_z
      - .offset:         296
        .size:           2
        .value_kind:     hidden_grid_dims
      - .offset:         320
        .size:           8
        .value_kind:     hidden_multigrid_sync_arg
      - .offset:         352
        .size:           4
        .value_kind:     hidden_dynamic_lds_size
    .group_segment_fixed_size: 0
    .kernarg_segment_align: 8
    .kernarg_segment_size: 488
    .language:       OpenCL C
    .language_version:
      - 2
      - 0
    .max_flat_workgroup_size: 512
    .name:           _Z14fwd_megakernel4Args
    .private_segment_fixed_size: 0
    .sgpr_count:     108
    .sgpr_spill_count: 7
    .symbol:         _Z14fwd_megakernel4Args.kd
    .uniform_work_group_size: 1
    .uses_dynamic_stack: false
    .vgpr_count:     255
    .vgpr_spill_count: 0
    .wavefront_size: 64
